# attention<false>: every wave runs mask-free key tiles; tiles outside the sequence are skipped by a scalar test, the +-64 window test of tiles 0/4 is folded into loop-invariant key offsets
# speedup vs baseline: 1.0426x; 1.0017x over previous
; #define LAS __attribute__((address_space(3)))
; #define ATTN_QLOAD(W) do { const bf16_t* qr_ = Qb + ((size_t)((W).b * 24 + (W).hd) * SEQ + (size_t)((W).r * (W).L + (W).i0 + 32 * wave + l31)) * 64; \
;         _Pragma("unroll") for (int ks_ = 0; ks_ < 4; ++ks_) qv[ks_] = *(const u32x4*)(qr_ + 16 * ks_ + 8 * h); } while (0)
; __device__ __forceinline__ void attn_issue(const AUnit& w, const bf16_t* Qb, const bf16_t* Kb, const bf16_t* Vb, int tid, int wave, int lane, u32x4 (&kv)[6], u32x4 (&vv)[6]) {
;     const int ch = tid & 7;
; #pragma unroll
;     for (int i = 0; i < 6; ++i) { const int row = (tid + 512 * i) >> 3; int pk = w.i0 - 64 + row; pk = pk < 0 ? 0 : (pk >= w.L ? w.L - 1 : pk);
;         const size_t off = ((size_t)(w.b * 24 + w.hd) * SEQ + (size_t)(w.r * w.L + pk)) * 64 + ch * 8; kv[i] = *(const u32x4*)(Kb + off); vv[i] = *(const u32x4*)(Vb + off); }
; }
; __device__ __forceinline__ float attn_tile_exp(f32x16& st, int j, float tlf, float bsl, float rlo, float rhi) {
;     float sum = 0.f;
; #pragma unroll
;     for (int i = 0; i < 16; ++i) { const float tmp = (float)(32 * j - 64 + (i & 3) + 8 * (i >> 2)) + tlf;
;         float arg = __builtin_fmaf(-bsl, __builtin_fabsf(tmp), st[i]);
;         arg = (tmp >= rlo && tmp <= rhi) ? arg : -1.0e30f;
;         const float pe = __builtin_amdgcn_exp2f(arg); st[i] = pe; sum += pe; }
;     return sum;
; }
; template <bool FUSED> __device__ __forceinline__ void attn_phase(const Args& a, LAS unsigned char* lds, int tid, int lane, int wave) {
;     constexpr int HD0 = FUSED ? 0 : 8, NH = FUSED ? 8 : 16, NU = 8 * NH * 32;
;     asm volatile("" : "+v"(tid), "+v"(lane));
;     bf16_t* Qb = (bf16_t*)(a.ws + WS_Q); const bf16_t* Kb = (const bf16_t*)(a.ws + WS_K); const bf16_t* Vb = (const bf16_t*)(a.ws + WS_V); float* LSE = (float*)(a.ws + WS_LSE);
;     const int h = lane >> 5, l31 = lane & 31;
;     const int q = (lane & 15) >> 2, p = lane & 3, blk = (lane >> 4) & 1;
;     int u = blockIdx.x;
;     u32x4 kv[6], vv[6], qv[4];
;     ...
;     if (u < NU) { const AUnit w0 = attn_decode(u, HD0, NH); attn_issue(w0, Qb, Kb, Vb, tid, wave, lane, kv, vv); ATTN_QLOAD(w0); }
.LBB0_277:
	s_or_b64 exec, exec, s[0:1]
	s_add_u32 s87, s52, 0xf00000
	s_addc_u32 s88, s53, 0
	s_add_u32 s58, s52, 0x26000000
	s_addc_u32 s59, s53, 0
	s_add_u32 s60, s52, 0x32000000
	s_addc_u32 s61, s53, 0
	s_add_u32 s62, s52, 0xf40000
	s_addc_u32 s63, s53, 0
	s_cmpk_lt_i32 s2, 0x1000
	s_waitcnt lgkmcnt(0)
	v_mov_b32_e32 v0, v186
	v_mov_b32_e32 v1, v178
	s_cselect_b64 s[64:65], -1, 0
	s_cmpk_gt_i32 s2, 0xfff
	s_barrier
	s_cbranch_scc1 .LBB0_286
	s_and_b32 s93, s2, 7
	s_lshl_b32 s93, s93, 5
	s_bfe_u32 s94, s2, 0x50003
	s_or_b32 s93, s93, s94
	s_andn2_b32 s94, s2, 0xff
	s_or_b32 s93, s93, s94
	s_cmpk_eq_i32 s54, 0x100
	s_cselect_b32 s93, s93, s2
	s_ashr_i32 s1, s93, 5
	s_lshr_b32 s4, s1, 28
	s_add_i32 s4, s1, s4
	s_and_b32 s4, s4, -16
	s_sub_i32 s1, s1, s4
	s_add_i32 s1, s1, 8
	s_ashr_i32 s5, s1, 2
	s_and_b32 s5, s5, -2
	s_lshr_b32 s6, 32, s5
	s_and_b32 s0, s93, 31
	s_lshr_b32 s7, 0x2000, s5
	s_sub_i32 s5, 5, s5
	s_add_i32 s6, s6, -1
	s_lshr_b32 s5, s0, s5
	s_and_b32 s0, s6, s0
	s_ashr_i32 s4, s93, 31
	s_lshl_b32 s6, s0, 8
	s_lshr_b32 s4, s4, 23
	v_lshlrev_b32_e32 v2, 3, v1
	v_ashrrev_i32_e32 v9, 3, v1
	s_sub_i32 s8, s6, 64
	s_add_i32 s4, s93, s4
	v_and_b32_e32 v144, 56, v2
	v_add_u32_e32 v2, s8, v9
	s_add_i32 s9, s7, -1
	s_ashr_i32 s4, s4, 9
	v_min_i32_e32 v3, s9, v2
	v_cmp_lt_i32_e32 vcc, -1, v2
	s_mul_i32 s4, s4, 24
	s_mul_i32 s7, s5, s7
	v_cndmask_b32_e32 v2, 0, v3, vcc
	s_add_i32 s0, s1, s4
	v_add_u32_e32 v2, s7, v2
	s_ashr_i32 s1, s0, 31
	v_ashrrev_i32_e32 v3, 31, v2
	s_lshl_b64 s[4:5], s[0:1], 19
	v_lshlrev_b64 v[2:3], 6, v[2:3]
	v_lshl_add_u64 v[2:3], v[2:3], 0, s[4:5]
	v_or_b32_e32 v2, v2, v144
	v_lshlrev_b64 v[2:3], 1, v[2:3]
	v_lshl_add_u64 v[4:5], s[58:59], 0, v[2:3]
	v_lshl_add_u64 v[2:3], s[60:61], 0, v[2:3]
	global_load_dwordx4 v[64:67], v[4:5], off
	global_load_dwordx4 v[68:71], v[2:3], off
	v_add_u32_e32 v2, 0x200, v1
	v_ashrrev_i32_e32 v10, 3, v2
	v_add_u32_e32 v2, s8, v10
	v_min_i32_e32 v3, s9, v2
	v_cmp_lt_i32_e32 vcc, -1, v2
	v_and_b32_e32 v7, 31, v0
	s_lshl_b64 s[0:1], s[0:1], 20
	v_cndmask_b32_e32 v2, 0, v3, vcc
	v_add_u32_e32 v2, s7, v2
	v_ashrrev_i32_e32 v3, 31, v2
	v_lshlrev_b64 v[2:3], 6, v[2:3]
	v_lshl_add_u64 v[2:3], v[2:3], 0, s[4:5]
	v_or_b32_e32 v2, v2, v144
	v_lshlrev_b64 v[2:3], 1, v[2:3]
	v_lshl_add_u64 v[4:5], s[58:59], 0, v[2:3]
	v_lshl_add_u64 v[2:3], s[60:61], 0, v[2:3]
	global_load_dwordx4 v[72:75], v[4:5], off
	global_load_dwordx4 v[76:79], v[2:3], off
	v_add_u32_e32 v2, 0x400, v1
	v_ashrrev_i32_e32 v11, 3, v2
	v_add_u32_e32 v2, s8, v11
	v_min_i32_e32 v3, s9, v2
	v_cmp_lt_i32_e32 vcc, -1, v2
	v_ashrrev_i32_e32 v8, 5, v0
	v_lshlrev_b32_e32 v148, 3, v8
	v_cndmask_b32_e32 v2, 0, v3, vcc
	v_add_u32_e32 v2, s7, v2
	v_ashrrev_i32_e32 v3, 31, v2
	v_lshlrev_b64 v[2:3], 6, v[2:3]
	v_lshl_add_u64 v[2:3], v[2:3], 0, s[4:5]
	v_or_b32_e32 v2, v2, v144
	v_lshlrev_b64 v[2:3], 1, v[2:3]
	v_lshl_add_u64 v[4:5], s[58:59], 0, v[2:3]
	v_lshl_add_u64 v[2:3], s[60:61], 0, v[2:3]
	global_load_dwordx4 v[80:83], v[4:5], off
	global_load_dwordx4 v[84:87], v[2:3], off
	v_add_u32_e32 v2, 0x600, v1
	v_ashrrev_i32_e32 v12, 3, v2
	v_add_u32_e32 v2, s8, v12
	v_min_i32_e32 v3, s9, v2
	v_cmp_lt_i32_e32 vcc, -1, v2
	v_ashrrev_i32_e32 v149, 31, v148
	v_lshrrev_b32_e32 v6, 2, v0
	v_cndmask_b32_e32 v2, 0, v3, vcc
	v_add_u32_e32 v2, s7, v2
	v_ashrrev_i32_e32 v3, 31, v2
	v_lshlrev_b64 v[2:3], 6, v[2:3]
	v_lshl_add_u64 v[2:3], v[2:3], 0, s[4:5]
	v_or_b32_e32 v2, v2, v144
	v_lshlrev_b64 v[2:3], 1, v[2:3]
	v_lshl_add_u64 v[4:5], s[58:59], 0, v[2:3]
	v_lshl_add_u64 v[2:3], s[60:61], 0, v[2:3]
	global_load_dwordx4 v[96:99], v[4:5], off
	global_load_dwordx4 v[104:107], v[2:3], off
	v_add_u32_e32 v2, 0x800, v1
	v_ashrrev_i32_e32 v13, 3, v2
	v_add_u32_e32 v2, s8, v13
	v_min_i32_e32 v3, s9, v2
	v_cmp_lt_i32_e32 vcc, -1, v2
	v_lshl_add_u32 v15, v8, 4, 0
	v_mov_b32_e32 v147, 0
	v_cndmask_b32_e32 v2, 0, v3, vcc
	v_add_u32_e32 v2, s7, v2
	v_ashrrev_i32_e32 v3, 31, v2
	v_lshlrev_b64 v[2:3], 6, v[2:3]
	v_lshl_add_u64 v[2:3], v[2:3], 0, s[4:5]
	v_or_b32_e32 v2, v2, v144
	v_lshlrev_b64 v[2:3], 1, v[2:3]
	v_lshl_add_u64 v[4:5], s[58:59], 0, v[2:3]
	v_lshl_add_u64 v[2:3], s[60:61], 0, v[2:3]
	global_load_dwordx4 v[112:115], v[4:5], off
	global_load_dwordx4 v[116:119], v[2:3], off
	v_add_u32_e32 v2, 0xa00, v1
	v_ashrrev_i32_e32 v14, 3, v2
	v_add_u32_e32 v2, s8, v14
	v_min_i32_e32 v3, s9, v2
	v_cmp_lt_i32_e32 vcc, -1, v2
	s_lshl_b32 s8, s85, 5
	s_movk_i32 s9, 0xc0
	v_cndmask_b32_e32 v2, 0, v3, vcc
	v_add_u32_e32 v2, s7, v2
	v_ashrrev_i32_e32 v3, 31, v2
	v_lshlrev_b64 v[2:3], 6, v[2:3]
	v_lshl_add_u64 v[2:3], v[2:3], 0, s[4:5]
	v_or_b32_e32 v2, v2, v144
	v_lshlrev_b64 v[2:3], 1, v[2:3]
	s_add_i32 s4, s6, s7
	v_lshl_add_u64 v[4:5], s[58:59], 0, v[2:3]
	v_lshl_add_u64 v[2:3], s[60:61], 0, v[2:3]
	s_add_i32 s4, s4, s8
	global_load_dwordx4 v[120:123], v[4:5], off
	global_load_dwordx4 v[124:127], v[2:3], off
	v_add_u32_e32 v2, s4, v7
	v_ashrrev_i32_e32 v3, 31, v2
	s_add_u32 s0, s40, s0
	s_addc_u32 s1, s41, s1
	v_lshlrev_b64 v[2:3], 7, v[2:3]
	v_lshl_add_u64 v[2:3], s[0:1], 0, v[2:3]
	v_lshl_add_u64 v[2:3], v[148:149], 1, v[2:3]
	global_load_dwordx4 v[88:91], v[2:3], off
	global_load_dwordx4 v[92:95], v[2:3], off offset:32
	global_load_dwordx4 v[100:103], v[2:3], off offset:64
	global_load_dwordx4 v[108:111], v[2:3], off offset:96
	v_mbcnt_hi_u32_b32 v2, -1, v187
	v_and_b32_e32 v4, 64, v2
	v_xor_b32_e32 v3, 32, v2
	v_add_u32_e32 v4, 64, v4
	v_cmp_lt_i32_e32 vcc, v3, v4
	v_lshlrev_b32_e32 v4, 3, v0
	s_lshl_b32 s0, s85, 12
	v_cndmask_b32_e32 v2, v2, v3, vcc
	v_lshlrev_b32_e32 v153, 2, v2
	v_lshlrev_b32_e32 v2, 2, v8
	v_sub_u32_e32 v175, v2, v7
	v_and_or_b32 v3, v6, 3, v2
; #define LAS __attribute__((address_space(3)))
; template <bool FUSED> __device__ __forceinline__ void attn_phase(const Args& a, LAS unsigned char* lds, int tid, int lane, int wave) {
;     ...
;         int tl = 4 * h - l31; asm volatile("" : "+v"(tl));
;         const float tlf = (float)tl;
;         const int lo_i = -iq > -64 ? -iq : -64, hi_i = (L - 1 - iq) < 64 ? (L - 1 - iq) : 64;
;         const float rlo = (float)lo_i, rhi = (float)hi_i;
;         const int wq0 = i0 + 32 * wave;
;         const bool edge = (wq0 < 64) || (wq0 + 32 > L - 64);
;         float sum = 0.f;
;         f32x16 o[2]; o[0] = f32x16{}; o[1] = f32x16{};
; #pragma unroll
;         for (int j = 0; j < 5; ++j) {
;             f32x16 st;
; #pragma unroll
;             for (int i = 0; i < 16; ++i) st[i] = -mb;
;             LAS const unsigned char* kp = lds + (32 * wave + 32 * j + l31) * KP + 16 * h;
; #pragma unroll
;             for (int ks = 0; ks < 4; ++ks) { const bf16x8 kf = *(LAS const bf16x8*)(kp + 32 * ks); st = __builtin_amdgcn_mfma_f32_32x32x16_bf16(kf, qf[ks], st, 0, 0, 0); }
;             sum += attn_tile_exp(st, j, tlf, bsl, rlo, rhi);
; #pragma unroll
;             for (int s2 = 0; s2 < 2; ++s2) { u32x4 pw; pw.x = pk2(st[8 * s2 + 0], st[8 * s2 + 1]); pw.y = pk2(st[8 * s2 + 2], st[8 * s2 + 3]); pw.z = pk2(st[8 * s2 + 4], st[8 * s2 + 5]); pw.w = pk2(st[8 * s2 + 6], st[8 * s2 + 7]);
;                 const bf16x8 pf = __builtin_bit_cast(bf16x8, pw);
;                 LAS const unsigned char* vp = lds + LDS_VOFF + (32 * wave + 32 * j + 16 * s2 + 4 * h + q) * VP + 32 * blk + 8 * p;
; #pragma unroll
;                 for (int dt = 0; dt < 2; ++dt) { const s16x4 lo = trrd(vp + dt * 64), hi = trrd(vp + 8 * VP + dt * 64);
;                     const bf16x8 vf = __builtin_shufflevector(lo, hi, 0, 1, 2, 3, 4, 5, 6, 7);
;                     o[dt] = __builtin_amdgcn_mfma_f32_32x32x16_bf16(vf, pf, o[dt], 0, 0, 0); } }
;             __builtin_amdgcn_sched_barrier(0);
;         }
;         sum += __shfl_xor(sum, 32);
;         if (un < NU) { const AUnit wq = attn_decode(un, HD0, NH); ATTN_QLOAD(wq); }
;         const float inv = __builtin_amdgcn_rcpf(sum);
;         {
;             u32x4 fo1[4], fo2[4], fg[4]; float fl1[4], fl2[4];
;             if constexpr (FUSED) {
;                 const bf16_t* Gb = (const bf16_t*)(a.ws + WS_G);
; #pragma unroll
	v_lshlrev_b32_e32 v2, 1, v0
	v_and_b32_e32 v2, 32, v2
	v_and_b32_e32 v6, 24, v4
	v_add3_u32 v16, 0, v2, v6
	v_lshlrev_b32_e32 v2, 6, v7
	s_add_i32 s0, s0, 0
	v_sub_co_u32_e32 v150, vcc, 0, v2
	s_add_i32 s6, s0, 0x1f800
	s_nop 0
	v_subb_co_u32_e64 v151, s[0:1], 0, 0, vcc
	v_and_b32_e32 v6, 8, v0
	v_cmp_eq_u32_e64 s[0:1], 0, v6
	v_add_u32_e32 v6, s8, v3
	s_add_i32 s10, s8, 32
	s_movk_i32 s7, 0x90
	v_mul_lo_u32 v25, v6, s9
	v_or_b32_e32 v6, s10, v7
	v_mul_lo_u32 v26, v6, s7
	v_add_u32_e32 v6, s10, v3
	s_add_i32 s10, s8, 64
	v_mul_lo_u32 v27, v6, s9
	v_or_b32_e32 v6, s10, v7
	v_mul_lo_u32 v28, v6, s7
	v_add_u32_e32 v6, s10, v3
	s_add_i32 s10, s8, 0x60
	v_or_b32_e32 v145, s8, v7
	v_mul_lo_u32 v29, v6, s9
	v_or_b32_e32 v6, s10, v7
	s_addk_i32 s8, 0x80
	v_mul_lo_u32 v30, v6, s7
	v_add_u32_e32 v6, s10, v3
	v_add_u32_e32 v3, s8, v3
	v_mul_lo_u32 v33, v3, s9
	v_bitop3_b32 v3, v8, v0, 15 bitop3:0x78
	v_lshlrev_b32_e32 v34, 3, v3
	v_add_u32_e32 v3, 2, v8
	v_bitop3_b32 v3, v3, v0, 15 bitop3:0x78
	v_lshlrev_b32_e32 v35, 3, v3
	v_add_u32_e32 v3, 4, v8
	v_bitop3_b32 v3, v3, v0, 15 bitop3:0x78
	v_lshlrev_b32_e32 v36, 3, v3
	v_add_u32_e32 v3, 6, v8
	v_bitop3_b32 v3, v3, v0, 15 bitop3:0x78
	v_lshlrev_b32_e32 v37, 3, v3
	v_add_u32_e32 v3, 8, v8
	v_bitop3_b32 v3, v3, v0, 15 bitop3:0x78
	v_lshlrev_b32_e32 v38, 3, v3
	v_add_u32_e32 v3, 10, v8
	v_bitop3_b32 v3, v3, v0, 15 bitop3:0x78
	v_lshlrev_b32_e32 v39, 3, v3
	v_add_u32_e32 v3, 12, v8
	v_bitop3_b32 v3, v3, v0, 15 bitop3:0x78
	v_lshlrev_b32_e32 v40, 3, v3
	v_add_u32_e32 v3, 14, v8
	v_ashrrev_i32_e32 v2, 3, v0
	v_bitop3_b32 v3, v3, v0, 15 bitop3:0x78
	v_lshlrev_b32_e32 v8, 3, v3
	v_lshrrev_b32_e32 v3, 1, v2
	v_xor_b32_e32 v3, v3, v0
	v_mul_lo_u32 v31, v6, s9
	v_or_b32_e32 v6, s8, v7
	v_lshlrev_b32_e32 v3, 4, v3
	v_mul_lo_u32 v32, v6, s7
	v_and_b32_e32 v42, 0x70, v3
	v_ashrrev_i32_e32 v3, 31, v2
	v_add_u32_e32 v6, 8, v2
	v_lshlrev_b64 v[156:157], 7, v[2:3]
	v_lshrrev_b32_e32 v3, 1, v6
	v_lshl_add_u32 v17, v7, 7, s6
	v_xor_b32_e32 v3, v3, v0
	v_ashrrev_i32_e32 v7, 31, v6
	v_lshl_add_u32 v41, v2, 7, s6
	v_lshl_add_u32 v43, v6, 7, s6
	v_lshlrev_b32_e32 v3, 4, v3
	v_lshlrev_b64 v[158:159], 7, v[6:7]
	v_add_u32_e32 v6, 16, v2
	v_add_u32_e32 v2, 24, v2
	v_and_b32_e32 v44, 0x70, v3
	v_lshrrev_b32_e32 v3, 1, v2
	v_cmp_gt_u32_e64 s[4:5], 32, v0
	v_xor_b32_e32 v0, v3, v0
	v_and_b32_e32 v1, 7, v1
	v_ashrrev_i32_e32 v7, 31, v6
	v_lshlrev_b32_e32 v0, 4, v0
	v_lshl_add_u32 v5, v1, 4, 0
	v_subrev_u32_e32 v155, 64, v9
	v_subrev_u32_e32 v170, 64, v10
	v_subrev_u32_e32 v171, 64, v11
	v_subrev_u32_e32 v172, 64, v12
	v_subrev_u32_e32 v173, 64, v13
	v_subrev_u32_e32 v174, 64, v14
	v_and_b32_e32 v4, 56, v4
	v_mul_lo_u32 v18, v9, s7
	v_mul_lo_u32 v9, v9, s9
	v_mul_lo_u32 v19, v10, s7
	v_mul_lo_u32 v10, v10, s9
	v_mul_lo_u32 v20, v11, s7
	v_mul_lo_u32 v11, v11, s9
	v_mul_lo_u32 v21, v12, s7
	v_mul_lo_u32 v12, v12, s9
	v_mul_lo_u32 v22, v13, s7
	v_mul_lo_u32 v13, v13, s9
	v_mul_lo_u32 v23, v14, s7
	v_mul_lo_u32 v14, v14, s9
	v_mul_lo_u32 v24, v145, s7
	v_lshl_add_u32 v45, v6, 7, s6
	v_lshlrev_b64 v[160:161], 7, v[6:7]
	v_lshl_add_u32 v6, v2, 7, s6
	v_and_b32_e32 v0, 0x70, v0
	v_ashrrev_i32_e32 v3, 31, v2
	v_lshlrev_b32_e32 v146, 5, v1
	s_movk_i32 s74, 0x60
	v_lshlrev_b64 v[162:163], 7, v[2:3]
	v_lshl_add_u64 v[164:165], s[44:45], 0, v[146:147]
	v_lshl_add_u64 v[166:167], v[148:149], 2, s[42:43]
	v_mov_b32_e32 v176, 0x358637bd
	v_add_u32_e32 v177, v5, v18
	v_add_u32_e32 v188, v5, v9
	v_add_u32_e32 v189, v5, v19
	v_add_u32_e32 v190, v5, v10
	v_add_u32_e32 v191, v5, v20
	v_add_u32_e32 v192, v5, v11
	v_add_u32_e32 v193, v5, v21
	v_add_u32_e32 v194, v5, v12
	v_add_u32_e32 v195, v5, v22
	v_add_u32_e32 v196, v5, v13
	v_add_u32_e32 v197, v5, v23
	v_add_u32_e32 v198, v5, v14
	v_add_u32_e32 v199, v15, v24
	v_add_u32_e32 v200, v16, v25
	v_add_u32_e32 v201, v15, v26
	v_add_u32_e32 v202, v16, v27
	v_add_u32_e32 v203, v15, v28
	v_add_u32_e32 v204, v16, v29
	v_add_u32_e32 v205, v15, v30
	v_add_u32_e32 v206, v16, v31
	v_add_u32_e32 v207, v15, v32
	v_add_u32_e32 v208, v16, v33
	v_add_u32_e32 v209, v17, v34
	v_add_u32_e32 v210, v17, v35
	v_add_u32_e32 v211, v17, v36
	v_add_u32_e32 v212, v17, v37
	v_add_u32_e32 v213, v17, v38
; __device__ __forceinline__ float attn_tile_exp(f32x16& st, int j, float tlf, float bsl, float rlo, float rhi) {
;     float sum = 0.f;
; #pragma unroll
;     for (int i = 0; i < 16; ++i) { const float tmp = (float)(32 * j - 64 + (i & 3) + 8 * (i >> 2)) + tlf;
;         float arg = __builtin_fmaf(-bsl, __builtin_fabsf(tmp), st[i]);
;         arg = (tmp >= rlo && tmp <= rhi) ? arg : -1.0e30f;
;         const float pe = __builtin_amdgcn_exp2f(arg); st[i] = pe; sum += pe; }
;     return sum;
; }
; template <bool FUSED> __device__ __forceinline__ void attn_phase(const Args& a, LAS unsigned char* lds, int tid, int lane, int wave) {
;     ...
;         int tl = 4 * h - l31; asm volatile("" : "+v"(tl));
;         const float tlf = (float)tl;
	v_add_u32_e32 v214, v17, v39
	v_add_u32_e32 v215, v17, v40
	v_add_u32_e32 v216, v17, v8
	v_lshlrev_b32_e32 v146, 1, v4
	v_add_u32_e32 v217, v41, v42
	v_add_u32_e32 v218, v43, v44
	v_add_u32_e32 v219, v45, v42
	v_add_u32_e32 v220, v6, v0
	v_mov_b32_e32 v221, 0xf149f2ca
	s_mov_b32 s67, s93
	v_cvt_f32_i32_e32 v0, v175
	s_mov_b32 s6, 0x42800000
	v_mov_b32_e32 v1, 0x7149f2ca
	v_add_f32_e32 v128, 0xc2800000, v0
	v_cmp_le_f32_e64 vcc, |v128|, s6
	s_nop 1
	v_cndmask_b32_e32 v128, v1, v128, vcc
	v_add_f32_e32 v129, 0xc27c0000, v0
	v_cmp_le_f32_e64 vcc, |v129|, s6
	s_nop 1
	v_cndmask_b32_e32 v129, v1, v129, vcc
	v_add_f32_e32 v130, 0xc2780000, v0
	v_cmp_le_f32_e64 vcc, |v130|, s6
	s_nop 1
	v_cndmask_b32_e32 v130, v1, v130, vcc
	v_add_f32_e32 v131, 0xc2740000, v0
	v_cmp_le_f32_e64 vcc, |v131|, s6
	s_nop 1
	v_cndmask_b32_e32 v131, v1, v131, vcc
	v_add_f32_e32 v132, 0xc2600000, v0
	v_cmp_le_f32_e64 vcc, |v132|, s6
	s_nop 1
	v_cndmask_b32_e32 v132, v1, v132, vcc
	v_add_f32_e32 v133, 0xc25c0000, v0
	v_cmp_le_f32_e64 vcc, |v133|, s6
	s_nop 1
	v_cndmask_b32_e32 v133, v1, v133, vcc
	v_add_f32_e32 v134, 0xc2580000, v0
	v_cmp_le_f32_e64 vcc, |v134|, s6
	s_nop 1
	v_cndmask_b32_e32 v134, v1, v134, vcc
	v_add_f32_e32 v135, 0xc2540000, v0
	v_cmp_le_f32_e64 vcc, |v135|, s6
	s_nop 1
	v_cndmask_b32_e32 v135, v1, v135, vcc
	v_add_f32_e32 v137, 0xc2400000, v0
	v_cmp_le_f32_e64 vcc, |v137|, s6
	s_nop 1
	v_cndmask_b32_e32 v137, v1, v137, vcc
	v_add_f32_e32 v138, 0xc23c0000, v0
	v_cmp_le_f32_e64 vcc, |v138|, s6
	s_nop 1
	v_cndmask_b32_e32 v138, v1, v138, vcc
	v_add_f32_e32 v139, 0xc2380000, v0
	v_cmp_le_f32_e64 vcc, |v139|, s6
	s_nop 1
	v_cndmask_b32_e32 v139, v1, v139, vcc
	v_add_f32_e32 v140, 0xc2340000, v0
	v_cmp_le_f32_e64 vcc, |v140|, s6
	s_nop 1
	v_cndmask_b32_e32 v140, v1, v140, vcc
	v_add_f32_e32 v141, 0xc2200000, v0
	v_cmp_le_f32_e64 vcc, |v141|, s6
	s_nop 1
	v_cndmask_b32_e32 v141, v1, v141, vcc
	v_add_f32_e32 v142, 0xc21c0000, v0
	v_cmp_le_f32_e64 vcc, |v142|, s6
	s_nop 1
	v_cndmask_b32_e32 v142, v1, v142, vcc
	v_add_f32_e32 v143, 0xc2180000, v0
	v_cmp_le_f32_e64 vcc, |v143|, s6
	s_nop 1
	v_cndmask_b32_e32 v143, v1, v143, vcc
	v_add_f32_e32 v243, 0xc2140000, v0
	v_cmp_le_f32_e64 vcc, |v243|, s6
	s_nop 1
	v_cndmask_b32_e32 v243, v1, v243, vcc
	v_add_f32_e32 v244, 0x42800000, v0
	v_cmp_le_f32_e64 vcc, |v244|, s6
	s_nop 1
	v_cndmask_b32_e32 v244, v1, v244, vcc
	v_add_f32_e32 v245, 0x42820000, v0
	v_cmp_le_f32_e64 vcc, |v245|, s6
	s_nop 1
	v_cndmask_b32_e32 v245, v1, v245, vcc
	v_add_f32_e32 v246, 0x42840000, v0
	v_cmp_le_f32_e64 vcc, |v246|, s6
	s_nop 1
	v_cndmask_b32_e32 v246, v1, v246, vcc
	v_add_f32_e32 v247, 0x42860000, v0
	v_cmp_le_f32_e64 vcc, |v247|, s6
	s_nop 1
	v_cndmask_b32_e32 v247, v1, v247, vcc
	v_add_f32_e32 v248, 0x42900000, v0
	v_cmp_le_f32_e64 vcc, |v248|, s6
	s_nop 1
	v_cndmask_b32_e32 v248, v1, v248, vcc
	v_add_f32_e32 v249, 0x42920000, v0
	v_cmp_le_f32_e64 vcc, |v249|, s6
	s_nop 1
	v_cndmask_b32_e32 v249, v1, v249, vcc
	v_add_f32_e32 v250, 0x42940000, v0
	v_cmp_le_f32_e64 vcc, |v250|, s6
	s_nop 1
	v_cndmask_b32_e32 v250, v1, v250, vcc
	v_add_f32_e32 v251, 0x42960000, v0
	v_cmp_le_f32_e64 vcc, |v251|, s6
	s_nop 1
	v_cndmask_b32_e32 v251, v1, v251, vcc
	v_add_f32_e32 v252, 0x42a00000, v0
	v_cmp_le_f32_e64 vcc, |v252|, s6
	s_nop 1
	v_cndmask_b32_e32 v252, v1, v252, vcc
	v_add_f32_e32 v253, 0x42a20000, v0
	v_cmp_le_f32_e64 vcc, |v253|, s6
	s_nop 1
	v_cndmask_b32_e32 v253, v1, v253, vcc
	v_add_f32_e32 v254, 0x42a40000, v0
	v_cmp_le_f32_e64 vcc, |v254|, s6
	s_nop 1
	v_cndmask_b32_e32 v254, v1, v254, vcc
	v_add_f32_e32 v255, 0x42a60000, v0
	v_cmp_le_f32_e64 vcc, |v255|, s6
	s_nop 1
	v_cndmask_b32_e32 v255, v1, v255, vcc
	v_add_f32_e32 v164, 0x42b00000, v0
	v_cmp_le_f32_e64 vcc, |v164|, s6
	s_nop 1
	v_cndmask_b32_e32 v164, v1, v164, vcc
	v_add_f32_e32 v165, 0x42b20000, v0
	v_cmp_le_f32_e64 vcc, |v165|, s6
	s_nop 1
	v_cndmask_b32_e32 v165, v1, v165, vcc
	v_add_f32_e32 v166, 0x42b40000, v0
	v_cmp_le_f32_e64 vcc, |v166|, s6
	s_nop 1
	v_cndmask_b32_e32 v166, v1, v166, vcc
	v_add_f32_e32 v167, 0x42b60000, v0
	v_cmp_le_f32_e64 vcc, |v167|, s6
	s_nop 1
	v_cndmask_b32_e32 v167, v1, v167, vcc
	s_branch .LBB0_280

; #define LAS __attribute__((address_space(3)))
; __device__ __forceinline__ unsigned pk2(float lo, float hi) { f32x2_t v = {lo, hi}; bf16x2_t b = __builtin_convertvector(v, bf16x2_t); return __builtin_bit_cast(unsigned, b); }
; template <bool FUSED> __device__ __forceinline__ void attn_phase(const Args& a, LAS unsigned char* lds, int tid, int lane, int wave) {
;     ...
;         const float bsl = __builtin_amdgcn_exp2f(-(float)(slot + 1)) * (float)w.dil * LOG2E;
;         int tl = 4 * h - l31; asm volatile("" : "+v"(tl));
;         const float tlf = (float)tl;
;         const int lo_i = -iq > -64 ? -iq : -64, hi_i = (L - 1 - iq) < 64 ? (L - 1 - iq) : 64;
;         const float rlo = (float)lo_i, rhi = (float)hi_i;
;         const int wq0 = i0 + 32 * wave;
;         const bool edge = (wq0 < 64) || (wq0 + 32 > L - 64);
;         float sum = 0.f;
;         f32x16 o[2]; o[0] = f32x16{}; o[1] = f32x16{};
; #pragma unroll
;         for (int j = 0; j < 5; ++j) {
;             f32x16 st;
; #pragma unroll
;             for (int i = 0; i < 16; ++i) st[i] = -mb;
;             LAS const unsigned char* kp = lds + (32 * wave + 32 * j + l31) * KP + 16 * h;
; #pragma unroll
;             for (int ks = 0; ks < 4; ++ks) { const bf16x8 kf = *(LAS const bf16x8*)(kp + 32 * ks); st = __builtin_amdgcn_mfma_f32_32x32x16_bf16(kf, qf[ks], st, 0, 0, 0); }
;             sum += attn_tile_exp(st, j, tlf, bsl, rlo, rhi);
; #pragma unroll
;             for (int s2 = 0; s2 < 2; ++s2) { u32x4 pw; pw.x = pk2(st[8 * s2 + 0], st[8 * s2 + 1]); pw.y = pk2(st[8 * s2 + 2], st[8 * s2 + 3]); pw.z = pk2(st[8 * s2 + 4], st[8 * s2 + 5]); pw.w = pk2(st[8 * s2 + 6], st[8 * s2 + 7]);
;                 const bf16x8 pf = __builtin_bit_cast(bf16x8, pw);
;                 LAS const unsigned char* vp = lds + LDS_VOFF + (32 * wave + 32 * j + 16 * s2 + 4 * h + q) * VP + 32 * blk + 8 * p;
; #pragma unroll
;                 for (int dt = 0; dt < 2; ++dt) { const s16x4 lo = trrd(vp + dt * 64), hi = trrd(vp + 8 * VP + dt * 64);
;                     const bf16x8 vf = __builtin_shufflevector(lo, hi, 0, 1, 2, 3, 4, 5, 6, 7);
;                     o[dt] = __builtin_amdgcn_mfma_f32_32x32x16_bf16(vf, pf, o[dt], 0, 0, 0); } }
;             __builtin_amdgcn_sched_barrier(0);
;         }
.Lattn1_join:
	v_xor_b32_e32 v0, 0x80000000, v222
	v_mov_b32_e32 v1, v0
	v_mov_b32_e32 v2, v0
	v_mov_b32_e32 v3, v0
	v_mov_b32_e32 v4, v0
	v_mov_b32_e32 v5, v0
	v_mov_b32_e32 v6, v0
	v_mov_b32_e32 v7, v0
	v_mov_b32_e32 v8, v0
	v_mov_b32_e32 v9, v0
	v_mov_b32_e32 v10, v0
	v_mov_b32_e32 v11, v0
	v_mov_b32_e32 v12, v0
	v_mov_b32_e32 v13, v0
	v_mov_b32_e32 v14, v0
	v_mov_b32_e32 v15, v0
	v_exp_f32_e64 v46, -v32
	s_waitcnt lgkmcnt(0)
	v_mfma_f32_32x32x16_bf16 v[16:31], v[38:41], v[88:91], v[0:15]
	ds_read_b128 v[38:41], v199 offset:64
	s_and_b32 s77, s67, 31
	ds_read_b128 v[32:35], v199 offset:96
	s_add_i32 s6, s6, -1
	s_and_b32 s6, s6, s77
	v_mfma_f32_32x32x16_bf16 v[16:31], v[42:45], v[92:95], v[16:31]
	s_lshr_b32 s76, 0x2000, s75
	v_lshl_add_u32 v168, s6, 8, v145
	s_lshl_b32 s6, 1, s75
	v_sub_u32_e32 v37, 0, v168
	v_cvt_f32_u32_e32 v42, s6
	v_cvt_f32_i32_e32 v225, v48
	v_max_i32_e32 v37, 0xffffffc0, v37
	s_waitcnt lgkmcnt(1)
	v_mfma_f32_32x32x16_bf16 v[16:31], v[38:41], v[100:103], v[16:31]
	v_xad_u32 v38, v168, -1, s76
	v_min_i32_e32 v38, 64, v38
	v_cvt_f32_i32_e32 v169, v37
	v_cvt_f32_i32_e32 v223, v38
	v_mul_f32_e32 v36, v46, v42
	v_mul_f32_e32 v224, 0xbfb8aa3b, v36
	s_waitcnt lgkmcnt(0)
	v_mfma_f32_32x32x16_bf16 v[16:31], v[32:35], v[108:111], v[16:31]
	v_readfirstlane_b32 s98, v168
	s_sub_i32 s99, s76, 64
	s_cmp_lt_i32 s98, 64
	s_cbranch_scc1 .Lattn1_skip0
	s_nop 5
	s_nop 1
	v_fma_f32 v16, v224, |v128|, v16
	v_fma_f32 v17, v224, |v129|, v17
	v_exp_f32_e32 v33, v17
	v_fma_f32 v17, v224, |v130|, v18
	v_exp_f32_e32 v34, v17
	v_fma_f32 v17, v224, |v131|, v19
	v_exp_f32_e32 v35, v17
	v_fma_f32 v17, v224, |v132|, v20
	v_exp_f32_e32 v36, v17
	v_fma_f32 v17, v224, |v133|, v21
	v_exp_f32_e32 v37, v17
	v_fma_f32 v17, v224, |v134|, v22
	v_exp_f32_e32 v32, v16
	v_exp_f32_e32 v38, v17
	v_fma_f32 v17, v224, |v135|, v23
	v_add_f32_e32 v16, 0, v32
	v_exp_f32_e32 v23, v17
	v_add_f32_e32 v16, v33, v16
	v_add_f32_e32 v16, v34, v16
	v_fma_f32 v17, v224, |v137|, v24
	v_add_f32_e32 v16, v35, v16
	v_add_f32_e32 v16, v36, v16
	v_exp_f32_e32 v52, v17
	v_add_f32_e32 v16, v37, v16
	v_add_f32_e32 v16, v38, v16
	v_add_f32_e32 v16, v23, v16
	v_add_f32_e32 v60, v52, v16
	v_fma_f32 v16, v224, |v138|, v25
	v_exp_f32_e32 v61, v16
	v_fma_f32 v16, v224, |v139|, v26
	v_exp_f32_e32 v62, v16
	v_fma_f32 v16, v224, |v140|, v27
	v_exp_f32_e32 v63, v16
	v_fma_f32 v16, v224, |v141|, v28
	v_exp_f32_e32 v226, v16
	v_fma_f32 v16, v224, |v142|, v29
	v_exp_f32_e32 v227, v16
	v_fma_f32 v20, v224, |v143|, v30
	ds_read_b64_tr_b16 v[16:17], v200 offset:55296
	ds_read_b64_tr_b16 v[18:19], v200 offset:56832
	ds_read_b64_tr_b16 v[26:27], v200 offset:56896
	ds_read_b64_tr_b16 v[24:25], v200 offset:55360
	v_exp_f32_e32 v228, v20
	v_cvt_pk_bf16_f32 v20, v32, v33
	v_cvt_pk_bf16_f32 v21, v34, v35
	v_cvt_pk_bf16_f32 v22, v36, v37
	v_cvt_pk_bf16_f32 v23, v38, v23
	s_waitcnt lgkmcnt(2)
	s_nop 0
	v_mfma_f32_32x32x16_bf16 v[32:47], v[16:19], v[20:23], 0
	v_fma_f32 v16, v224, |v243|, v31
	v_mov_b32_e32 v53, v16
	ds_read_b64_tr_b16 v[48:49], v200 offset:58368
	ds_read_b64_tr_b16 v[50:51], v200 offset:59904
	v_exp_f32_e32 v229, v53
	ds_read_b64_tr_b16 v[58:59], v200 offset:59968
	ds_read_b64_tr_b16 v[56:57], v200 offset:58432
	v_cvt_pk_bf16_f32 v52, v52, v61
	s_waitcnt lgkmcnt(4)
	v_mfma_f32_32x32x16_bf16 v[16:31], v[24:27], v[20:23], 0
	v_cvt_pk_bf16_f32 v53, v62, v63
	v_cvt_pk_bf16_f32 v54, v226, v227
	v_cvt_pk_bf16_f32 v55, v228, v229
	s_waitcnt lgkmcnt(2)
	s_nop 0
	v_mfma_f32_32x32x16_bf16 v[32:47], v[48:51], v[52:55], v[32:47]
	v_add_f32_e32 v48, v61, v60
	v_add_f32_e32 v48, v62, v48
	v_add_f32_e32 v48, v63, v48
	v_add_f32_e32 v48, v226, v48
	v_add_f32_e32 v48, v227, v48
	v_add_f32_e32 v48, v228, v48
	v_add_f32_e32 v48, v229, v48
	s_waitcnt lgkmcnt(0)
	v_mfma_f32_32x32x16_bf16 v[16:31], v[56:59], v[52:55], v[16:31]
	v_add_f32_e32 v238, 0, v48
	s_branch .Lattn1_t1
.Lattn1_skip0:
	v_mov_b32_e32 v32, 0
	v_mov_b32_e32 v33, 0
	v_mov_b32_e32 v34, 0
	v_mov_b32_e32 v35, 0
	v_mov_b32_e32 v36, 0
	v_mov_b32_e32 v37, 0
	v_mov_b32_e32 v38, 0
	v_mov_b32_e32 v39, 0
	v_mov_b32_e32 v40, 0
	v_mov_b32_e32 v41, 0
	v_mov_b32_e32 v42, 0
	v_mov_b32_e32 v43, 0
	v_mov_b32_e32 v44, 0
	v_mov_b32_e32 v45, 0
	v_mov_b32_e32 v46, 0
	v_mov_b32_e32 v47, 0
	v_mov_b32_e32 v238, 0
	s_nop 3
	v_mov_b32_e32 v16, 0
	v_mov_b32_e32 v17, 0
	v_mov_b32_e32 v18, 0
	v_mov_b32_e32 v19, 0
	v_mov_b32_e32 v20, 0
	v_mov_b32_e32 v21, 0
	v_mov_b32_e32 v22, 0
	v_mov_b32_e32 v23, 0
	v_mov_b32_e32 v24, 0
	v_mov_b32_e32 v25, 0
	v_mov_b32_e32 v26, 0
	v_mov_b32_e32 v27, 0
	v_mov_b32_e32 v28, 0
	v_mov_b32_e32 v29, 0
	v_mov_b32_e32 v30, 0
	v_mov_b32_e32 v31, 0
; #define LAS __attribute__((address_space(3)))
; __device__ __forceinline__ unsigned pk2(float lo, float hi) { f32x2_t v = {lo, hi}; bf16x2_t b = __builtin_convertvector(v, bf16x2_t); return __builtin_bit_cast(unsigned, b); }
; __device__ __forceinline__ s16x4 trrd(LAS const unsigned char* p) { return __builtin_bit_cast(s16x4, __builtin_amdgcn_ds_read_tr16_b64_v4i16((LAS v4i16_t*)p)); }
; template <bool FUSED> __device__ __forceinline__ void attn_phase(const Args& a, LAS unsigned char* lds, int tid, int lane, int wave) {
;     ...
;         for (int j = 0; j < 5; ++j) {
;             f32x16 st;
; #pragma unroll
;             for (int i = 0; i < 16; ++i) st[i] = -mb;
;             LAS const unsigned char* kp = lds + (32 * wave + 32 * j + l31) * KP + 16 * h;
; #pragma unroll
;             for (int ks = 0; ks < 4; ++ks) { const bf16x8 kf = *(LAS const bf16x8*)(kp + 32 * ks); st = __builtin_amdgcn_mfma_f32_32x32x16_bf16(kf, qf[ks], st, 0, 0, 0); }
;             sum += attn_tile_exp(st, j, tlf, bsl, rlo, rhi);
; #pragma unroll
;             for (int s2 = 0; s2 < 2; ++s2) { u32x4 pw; pw.x = pk2(st[8 * s2 + 0], st[8 * s2 + 1]); pw.y = pk2(st[8 * s2 + 2], st[8 * s2 + 3]); pw.z = pk2(st[8 * s2 + 4], st[8 * s2 + 5]); pw.w = pk2(st[8 * s2 + 6], st[8 * s2 + 7]);
;                 const bf16x8 pf = __builtin_bit_cast(bf16x8, pw);
;                 LAS const unsigned char* vp = lds + LDS_VOFF + (32 * wave + 32 * j + 16 * s2 + 4 * h + q) * VP + 32 * blk + 8 * p;
; #pragma unroll
;                 for (int dt = 0; dt < 2; ++dt) { const s16x4 lo = trrd(vp + dt * 64), hi = trrd(vp + 8 * VP + dt * 64);
;                     const bf16x8 vf = __builtin_shufflevector(lo, hi, 0, 1, 2, 3, 4, 5, 6, 7);
;                     o[dt] = __builtin_amdgcn_mfma_f32_32x32x16_bf16(vf, pf, o[dt], 0, 0, 0); } }
;             __builtin_amdgcn_sched_barrier(0);
;         }
.Lattn1_t1:
	s_cmp_lt_i32 s98, 32
	s_cbranch_scc1 .Lattn1_skip1
	ds_read_b128 v[226:229], v201
	ds_read_b128 v[230:233], v201 offset:32
	v_add_f32_e32 v239, 0xc2000000, v225
	v_add_f32_e32 v240, 0xc1f80000, v225
	s_waitcnt lgkmcnt(1)
	v_mfma_f32_32x32x16_bf16 v[48:63], v[226:229], v[88:91], v[0:15]
	ds_read_b128 v[226:229], v201 offset:64
	ds_read_b128 v[234:237], v201 offset:96
	v_add_f32_e32 v241, 0xc1f00000, v225
	v_add_f32_e32 v242, 0xc1e80000, v225
	s_waitcnt lgkmcnt(2)
	v_mfma_f32_32x32x16_bf16 v[48:63], v[230:233], v[92:95], v[48:63]
	v_add_f32_e32 v230, 0xc1c00000, v225
	v_add_f32_e32 v231, 0xc1b80000, v225
	s_waitcnt lgkmcnt(1)
	v_mfma_f32_32x32x16_bf16 v[48:63], v[226:229], v[100:103], v[48:63]
	s_waitcnt lgkmcnt(0)
	v_mfma_f32_32x32x16_bf16 v[48:63], v[234:237], v[108:111], v[48:63]
	s_nop 11
	v_fma_f32 v48, v224, |v239|, v48
	v_fma_f32 v49, v224, |v240|, v49
	v_fma_f32 v50, v224, |v241|, v50
	v_fma_f32 v51, v224, |v242|, v51
	v_fma_f32 v52, v224, |v230|, v52
	v_fma_f32 v53, v224, |v231|, v53
	v_exp_f32_e32 v227, v49
	v_mov_b32_e32 v49, v53
	v_exp_f32_e32 v231, v49
	v_add_f32_e32 v49, 0xc1b00000, v225
	v_exp_f32_e32 v228, v50
	v_fma_f32 v49, v224, |v49|, v54
	v_exp_f32_e32 v226, v48
	v_exp_f32_e32 v232, v49
	v_add_f32_e32 v49, 0xc1a80000, v225
	v_fma_f32 v49, v224, |v49|, v55
	v_exp_f32_e32 v229, v51
	v_exp_f32_e32 v230, v52
	v_add_f32_e32 v48, 0, v226
	v_exp_f32_e32 v55, v49
	v_add_f32_e32 v49, 0xc1800000, v225
	v_add_f32_e32 v48, v227, v48
	v_add_f32_e32 v48, v228, v48
	v_fma_f32 v49, v224, |v49|, v56
	v_add_f32_e32 v48, v229, v48
	v_add_f32_e32 v48, v230, v48
	v_exp_f32_e32 v233, v49
	v_add_f32_e32 v48, v231, v48
	v_add_f32_e32 v48, v232, v48
	v_add_f32_e32 v48, v55, v48
	v_add_f32_e32 v234, v233, v48
	v_add_f32_e32 v48, 0xc1700000, v225
	v_fma_f32 v48, v224, |v48|, v57
	v_exp_f32_e32 v235, v48
	v_add_f32_e32 v48, 0xc1600000, v225
	v_fma_f32 v48, v224, |v48|, v58
	v_exp_f32_e32 v236, v48
	v_add_f32_e32 v48, 0xc1500000, v225
	v_fma_f32 v48, v224, |v48|, v59
	v_exp_f32_e32 v237, v48
	v_add_f32_e32 v48, 0xc1000000, v225
	v_fma_f32 v48, v224, |v48|, v60
	v_exp_f32_e32 v60, v48
	v_add_f32_e32 v48, 0xc0e00000, v225
	v_fma_f32 v48, v224, |v48|, v61
	v_exp_f32_e32 v61, v48
	v_add_f32_e32 v48, 0xc0c00000, v225
	v_fma_f32 v52, v224, |v48|, v62
	ds_read_b64_tr_b16 v[48:49], v202 offset:55296
	ds_read_b64_tr_b16 v[50:51], v202 offset:56832
	ds_read_b64_tr_b16 v[58:59], v202 offset:56896
	ds_read_b64_tr_b16 v[56:57], v202 offset:55360
	v_exp_f32_e32 v62, v52
	v_add_f32_e32 v239, 0xc0a00000, v225
	v_cvt_pk_bf16_f32 v52, v226, v227
	v_cvt_pk_bf16_f32 v53, v228, v229
	v_cvt_pk_bf16_f32 v54, v230, v231
	v_cvt_pk_bf16_f32 v55, v232, v55
	s_waitcnt lgkmcnt(2)
	s_nop 0
	v_mfma_f32_32x32x16_bf16 v[32:47], v[48:51], v[52:55], v[32:47]
	v_fma_f32 v63, v224, |v239|, v63
	ds_read_b64_tr_b16 v[48:49], v202 offset:58368
	ds_read_b64_tr_b16 v[50:51], v202 offset:59904
	v_exp_f32_e32 v63, v63
	s_waitcnt lgkmcnt(2)
	v_mfma_f32_32x32x16_bf16 v[16:31], v[56:59], v[52:55], v[16:31]
	ds_read_b64_tr_b16 v[58:59], v202 offset:59968
	ds_read_b64_tr_b16 v[56:57], v202 offset:58432
	v_cvt_pk_bf16_f32 v52, v233, v235
	v_cvt_pk_bf16_f32 v53, v236, v237
	v_cvt_pk_bf16_f32 v54, v60, v61
	v_cvt_pk_bf16_f32 v55, v62, v63
	s_waitcnt lgkmcnt(2)
	s_nop 0
	v_mfma_f32_32x32x16_bf16 v[32:47], v[48:51], v[52:55], v[32:47]
	v_add_f32_e32 v48, v235, v234
	v_add_f32_e32 v48, v236, v48
	v_add_f32_e32 v48, v237, v48
	v_add_f32_e32 v48, v60, v48
	v_add_f32_e32 v48, v61, v48
	v_add_f32_e32 v48, v62, v48
	v_add_f32_e32 v48, v63, v48
	s_waitcnt lgkmcnt(0)
	v_mfma_f32_32x32x16_bf16 v[16:31], v[56:59], v[52:55], v[16:31]
	v_add_f32_e32 v238, v238, v48
.Lattn1_skip1:
	ds_read_b128 v[226:229], v203
	ds_read_b128 v[230:233], v203 offset:32
	v_add_f32_e32 v239, 1.0, v225
	s_waitcnt lgkmcnt(1)
	v_mfma_f32_32x32x16_bf16 v[48:63], v[226:229], v[88:91], v[0:15]
	ds_read_b128 v[226:229], v203 offset:64
	ds_read_b128 v[234:237], v203 offset:96
	s_waitcnt lgkmcnt(2)
	v_mfma_f32_32x32x16_bf16 v[48:63], v[230:233], v[92:95], v[48:63]
	v_add_f32_e32 v230, 2.0, v225
	v_add_f32_e32 v231, 0x40400000, v225
	v_add_f32_e32 v232, 0x41000000, v225
	s_waitcnt lgkmcnt(1)
	v_mfma_f32_32x32x16_bf16 v[48:63], v[226:229], v[100:103], v[48:63]
	v_add_f32_e32 v233, 0x41100000, v225
	s_waitcnt lgkmcnt(0)
	v_mfma_f32_32x32x16_bf16 v[48:63], v[234:237], v[108:111], v[48:63]
	s_nop 11
	v_fma_f32 v48, v224, |v225|, v48
	v_fma_f32 v49, v224, |v239|, v49
	v_fma_f32 v50, v224, |v230|, v50
	v_fma_f32 v51, v224, |v231|, v51
	v_fma_f32 v52, v224, |v232|, v52
	v_fma_f32 v53, v224, |v233|, v53
	v_exp_f32_e32 v227, v49
	v_mov_b32_e32 v49, v53
	v_exp_f32_e32 v231, v49
	v_add_f32_e32 v49, 0x41200000, v225
	v_exp_f32_e32 v228, v50
	v_fma_f32 v49, v224, |v49|, v54
	v_exp_f32_e32 v226, v48
	v_exp_f32_e32 v232, v49
	v_add_f32_e32 v49, 0x41300000, v225
	v_fma_f32 v49, v224, |v49|, v55
	v_exp_f32_e32 v229, v51
	v_exp_f32_e32 v230, v52
	v_add_f32_e32 v48, 0, v226
	v_exp_f32_e32 v55, v49
	v_add_f32_e32 v49, 0x41800000, v225
	v_add_f32_e32 v48, v227, v48
	v_add_f32_e32 v48, v228, v48
	v_fma_f32 v49, v224, |v49|, v56
	v_add_f32_e32 v48, v229, v48
	v_add_f32_e32 v48, v230, v48
	v_exp_f32_e32 v233, v49
	v_add_f32_e32 v48, v231, v48
	v_add_f32_e32 v48, v232, v48
	v_add_f32_e32 v48, v55, v48
	v_add_f32_e32 v234, v233, v48
	v_add_f32_e32 v48, 0x41880000, v225
	v_fma_f32 v48, v224, |v48|, v57
	v_exp_f32_e32 v235, v48
	v_add_f32_e32 v48, 0x41900000, v225
	v_fma_f32 v48, v224, |v48|, v58
	v_exp_f32_e32 v236, v48
	v_add_f32_e32 v48, 0x41980000, v225
	v_fma_f32 v48, v224, |v48|, v59
	v_exp_f32_e32 v237, v48
	v_add_f32_e32 v48, 0x41c00000, v225
	v_fma_f32 v48, v224, |v48|, v60
	v_exp_f32_e32 v60, v48
	v_add_f32_e32 v48, 0x41c80000, v225
	v_fma_f32 v48, v224, |v48|, v61
	v_exp_f32_e32 v61, v48
	v_add_f32_e32 v48, 0x41d00000, v225
	v_fma_f32 v52, v224, |v48|, v62
	ds_read_b64_tr_b16 v[48:49], v204 offset:55296
	ds_read_b64_tr_b16 v[50:51], v204 offset:56832
	ds_read_b64_tr_b16 v[58:59], v204 offset:56896
	ds_read_b64_tr_b16 v[56:57], v204 offset:55360
	v_exp_f32_e32 v62, v52
	v_add_f32_e32 v239, 0x41d80000, v225
	v_cvt_pk_bf16_f32 v52, v226, v227
	v_cvt_pk_bf16_f32 v53, v228, v229
	v_cvt_pk_bf16_f32 v54, v230, v231
	v_cvt_pk_bf16_f32 v55, v232, v55
	s_waitcnt lgkmcnt(2)
; #define LAS __attribute__((address_space(3)))
; __device__ __forceinline__ unsigned pk2(float lo, float hi) { f32x2_t v = {lo, hi}; bf16x2_t b = __builtin_convertvector(v, bf16x2_t); return __builtin_bit_cast(unsigned, b); }
; __device__ __forceinline__ s16x4 trrd(LAS const unsigned char* p) { return __builtin_bit_cast(s16x4, __builtin_amdgcn_ds_read_tr16_b64_v4i16((LAS v4i16_t*)p)); }
; template <bool FUSED> __device__ __forceinline__ void attn_phase(const Args& a, LAS unsigned char* lds, int tid, int lane, int wave) {
;     ...
;         for (int j = 0; j < 5; ++j) {
;             f32x16 st;
; #pragma unroll
;             for (int i = 0; i < 16; ++i) st[i] = -mb;
;             LAS const unsigned char* kp = lds + (32 * wave + 32 * j + l31) * KP + 16 * h;
; #pragma unroll
;             for (int ks = 0; ks < 4; ++ks) { const bf16x8 kf = *(LAS const bf16x8*)(kp + 32 * ks); st = __builtin_amdgcn_mfma_f32_32x32x16_bf16(kf, qf[ks], st, 0, 0, 0); }
;             sum += attn_tile_exp(st, j, tlf, bsl, rlo, rhi);
; #pragma unroll
;             for (int s2 = 0; s2 < 2; ++s2) { u32x4 pw; pw.x = pk2(st[8 * s2 + 0], st[8 * s2 + 1]); pw.y = pk2(st[8 * s2 + 2], st[8 * s2 + 3]); pw.z = pk2(st[8 * s2 + 4], st[8 * s2 + 5]); pw.w = pk2(st[8 * s2 + 6], st[8 * s2 + 7]);
;                 const bf16x8 pf = __builtin_bit_cast(bf16x8, pw);
;                 LAS const unsigned char* vp = lds + LDS_VOFF + (32 * wave + 32 * j + 16 * s2 + 4 * h + q) * VP + 32 * blk + 8 * p;
; #pragma unroll
;                 for (int dt = 0; dt < 2; ++dt) { const s16x4 lo = trrd(vp + dt * 64), hi = trrd(vp + 8 * VP + dt * 64);
;                     const bf16x8 vf = __builtin_shufflevector(lo, hi, 0, 1, 2, 3, 4, 5, 6, 7);
;                     o[dt] = __builtin_amdgcn_mfma_f32_32x32x16_bf16(vf, pf, o[dt], 0, 0, 0); } }
;             __builtin_amdgcn_sched_barrier(0);
;         }
	s_nop 0
	v_mfma_f32_32x32x16_bf16 v[32:47], v[48:51], v[52:55], v[32:47]
	v_fma_f32 v63, v224, |v239|, v63
	ds_read_b64_tr_b16 v[48:49], v204 offset:58368
	ds_read_b64_tr_b16 v[50:51], v204 offset:59904
	v_exp_f32_e32 v63, v63
	s_waitcnt lgkmcnt(2)
	v_mfma_f32_32x32x16_bf16 v[16:31], v[56:59], v[52:55], v[16:31]
	ds_read_b64_tr_b16 v[58:59], v204 offset:59968
	ds_read_b64_tr_b16 v[56:57], v204 offset:58432
	v_cvt_pk_bf16_f32 v52, v233, v235
	v_cvt_pk_bf16_f32 v53, v236, v237
	v_cvt_pk_bf16_f32 v54, v60, v61
	v_cvt_pk_bf16_f32 v55, v62, v63
	s_waitcnt lgkmcnt(2)
	s_nop 0
	v_mfma_f32_32x32x16_bf16 v[32:47], v[48:51], v[52:55], v[32:47]
	v_add_f32_e32 v48, v235, v234
	v_add_f32_e32 v48, v236, v48
	v_add_f32_e32 v48, v237, v48
	v_add_f32_e32 v48, v60, v48
	v_add_f32_e32 v48, v61, v48
	v_add_f32_e32 v48, v62, v48
	v_add_f32_e32 v48, v63, v48
	s_waitcnt lgkmcnt(0)
	v_mfma_f32_32x32x16_bf16 v[16:31], v[56:59], v[52:55], v[16:31]
	v_add_f32_e32 v238, v238, v48
	s_cmp_gt_i32 s98, s99
	s_cbranch_scc1 .Lattn1_skip3
	ds_read_b128 v[226:229], v205
	ds_read_b128 v[230:233], v205 offset:32
	v_add_f32_e32 v239, 0x42000000, v225
	v_add_f32_e32 v240, 0x42040000, v225
	s_waitcnt lgkmcnt(1)
	v_mfma_f32_32x32x16_bf16 v[48:63], v[226:229], v[88:91], v[0:15]
	ds_read_b128 v[226:229], v205 offset:64
	ds_read_b128 v[234:237], v205 offset:96
	v_add_f32_e32 v241, 0x42080000, v225
	v_add_f32_e32 v242, 0x420c0000, v225
	s_waitcnt lgkmcnt(2)
	v_mfma_f32_32x32x16_bf16 v[48:63], v[230:233], v[92:95], v[48:63]
	v_add_f32_e32 v230, 0x42200000, v225
	v_add_f32_e32 v231, 0x42240000, v225
	s_waitcnt lgkmcnt(1)
	v_mfma_f32_32x32x16_bf16 v[48:63], v[226:229], v[100:103], v[48:63]
	s_waitcnt lgkmcnt(0)
	v_mfma_f32_32x32x16_bf16 v[48:63], v[234:237], v[108:111], v[48:63]
	s_nop 11
	v_fma_f32 v48, v224, |v239|, v48
	v_fma_f32 v49, v224, |v240|, v49
	v_fma_f32 v50, v224, |v241|, v50
	v_fma_f32 v51, v224, |v242|, v51
	v_fma_f32 v52, v224, |v230|, v52
	v_fma_f32 v53, v224, |v231|, v53
	v_exp_f32_e32 v227, v49
	v_mov_b32_e32 v49, v53
	v_exp_f32_e32 v231, v49
	v_add_f32_e32 v49, 0x42280000, v225
	v_exp_f32_e32 v228, v50
	v_fma_f32 v49, v224, |v49|, v54
	v_exp_f32_e32 v226, v48
	v_exp_f32_e32 v232, v49
	v_add_f32_e32 v49, 0x422c0000, v225
	v_fma_f32 v49, v224, |v49|, v55
	v_exp_f32_e32 v229, v51
	v_exp_f32_e32 v230, v52
	v_add_f32_e32 v48, 0, v226
	v_exp_f32_e32 v55, v49
	v_add_f32_e32 v49, 0x42400000, v225
	v_add_f32_e32 v48, v227, v48
	v_add_f32_e32 v48, v228, v48
	v_fma_f32 v49, v224, |v49|, v56
	v_add_f32_e32 v48, v229, v48
	v_add_f32_e32 v48, v230, v48
	v_exp_f32_e32 v233, v49
	v_add_f32_e32 v48, v231, v48
	v_add_f32_e32 v48, v232, v48
	v_add_f32_e32 v48, v55, v48
	v_add_f32_e32 v234, v233, v48
	v_add_f32_e32 v48, 0x42440000, v225
	v_fma_f32 v48, v224, |v48|, v57
	v_exp_f32_e32 v235, v48
	v_add_f32_e32 v48, 0x42480000, v225
	v_fma_f32 v48, v224, |v48|, v58
	v_exp_f32_e32 v236, v48
	v_add_f32_e32 v48, 0x424c0000, v225
	v_fma_f32 v48, v224, |v48|, v59
	v_exp_f32_e32 v237, v48
	v_add_f32_e32 v48, 0x42600000, v225
	v_fma_f32 v48, v224, |v48|, v60
	v_exp_f32_e32 v60, v48
	v_add_f32_e32 v48, 0x42640000, v225
	v_fma_f32 v48, v224, |v48|, v61
	v_exp_f32_e32 v61, v48
	v_add_f32_e32 v48, 0x42680000, v225
	v_fma_f32 v52, v224, |v48|, v62
	ds_read_b64_tr_b16 v[48:49], v206 offset:55296
	ds_read_b64_tr_b16 v[50:51], v206 offset:56832
	ds_read_b64_tr_b16 v[58:59], v206 offset:56896
	ds_read_b64_tr_b16 v[56:57], v206 offset:55360
	v_exp_f32_e32 v62, v52
	v_add_f32_e32 v239, 0x426c0000, v225
	v_cvt_pk_bf16_f32 v52, v226, v227
	v_cvt_pk_bf16_f32 v53, v228, v229
	v_cvt_pk_bf16_f32 v54, v230, v231
	v_cvt_pk_bf16_f32 v55, v232, v55
	s_waitcnt lgkmcnt(2)
	s_nop 0
	v_mfma_f32_32x32x16_bf16 v[32:47], v[48:51], v[52:55], v[32:47]
	v_fma_f32 v63, v224, |v239|, v63
	ds_read_b64_tr_b16 v[48:49], v206 offset:58368
	ds_read_b64_tr_b16 v[50:51], v206 offset:59904
	v_exp_f32_e32 v63, v63
	s_waitcnt lgkmcnt(2)
	v_mfma_f32_32x32x16_bf16 v[16:31], v[56:59], v[52:55], v[16:31]
	ds_read_b64_tr_b16 v[58:59], v206 offset:59968
	ds_read_b64_tr_b16 v[56:57], v206 offset:58432
	v_cvt_pk_bf16_f32 v52, v233, v235
	v_cvt_pk_bf16_f32 v53, v236, v237
	v_cvt_pk_bf16_f32 v54, v60, v61
	v_cvt_pk_bf16_f32 v55, v62, v63
	s_waitcnt lgkmcnt(2)
	s_nop 0
	v_mfma_f32_32x32x16_bf16 v[32:47], v[48:51], v[52:55], v[32:47]
	v_add_f32_e32 v48, v235, v234
	v_add_f32_e32 v48, v236, v48
	v_add_f32_e32 v48, v237, v48
	v_add_f32_e32 v48, v60, v48
	v_add_f32_e32 v48, v61, v48
	v_add_f32_e32 v48, v62, v48
	v_add_f32_e32 v48, v63, v48
	s_waitcnt lgkmcnt(0)
	v_mfma_f32_32x32x16_bf16 v[16:31], v[56:59], v[52:55], v[16:31]
	v_add_f32_e32 v60, v238, v48
	s_branch .Lattn1_t4f
; #define LAS __attribute__((address_space(3)))
; __device__ __forceinline__ unsigned pk2(float lo, float hi) { f32x2_t v = {lo, hi}; bf16x2_t b = __builtin_convertvector(v, bf16x2_t); return __builtin_bit_cast(unsigned, b); }
; __device__ __forceinline__ s16x4 trrd(LAS const unsigned char* p) { return __builtin_bit_cast(s16x4, __builtin_amdgcn_ds_read_tr16_b64_v4i16((LAS v4i16_t*)p)); }
; #define ATTN_QLOAD(W) do { const bf16_t* qr_ = Qb + ((size_t)((W).b * 24 + (W).hd) * SEQ + (size_t)((W).r * (W).L + (W).i0 + 32 * wave + l31)) * 64; \
;         _Pragma("unroll") for (int ks_ = 0; ks_ < 4; ++ks_) qv[ks_] = *(const u32x4*)(qr_ + 16 * ks_ + 8 * h); } while (0)
; template <bool FUSED> __device__ __forceinline__ void attn_phase(const Args& a, LAS unsigned char* lds, int tid, int lane, int wave) {
;     ...
;         for (int j = 0; j < 5; ++j) {
;             f32x16 st;
; #pragma unroll
;             for (int i = 0; i < 16; ++i) st[i] = -mb;
;             LAS const unsigned char* kp = lds + (32 * wave + 32 * j + l31) * KP + 16 * h;
; #pragma unroll
;             for (int ks = 0; ks < 4; ++ks) { const bf16x8 kf = *(LAS const bf16x8*)(kp + 32 * ks); st = __builtin_amdgcn_mfma_f32_32x32x16_bf16(kf, qf[ks], st, 0, 0, 0); }
;             sum += attn_tile_exp(st, j, tlf, bsl, rlo, rhi);
; #pragma unroll
;             for (int s2 = 0; s2 < 2; ++s2) { u32x4 pw; pw.x = pk2(st[8 * s2 + 0], st[8 * s2 + 1]); pw.y = pk2(st[8 * s2 + 2], st[8 * s2 + 3]); pw.z = pk2(st[8 * s2 + 4], st[8 * s2 + 5]); pw.w = pk2(st[8 * s2 + 6], st[8 * s2 + 7]);
;                 const bf16x8 pf = __builtin_bit_cast(bf16x8, pw);
;                 LAS const unsigned char* vp = lds + LDS_VOFF + (32 * wave + 32 * j + 16 * s2 + 4 * h + q) * VP + 32 * blk + 8 * p;
; #pragma unroll
;                 for (int dt = 0; dt < 2; ++dt) { const s16x4 lo = trrd(vp + dt * 64), hi = trrd(vp + 8 * VP + dt * 64);
;                     const bf16x8 vf = __builtin_shufflevector(lo, hi, 0, 1, 2, 3, 4, 5, 6, 7);
;                     o[dt] = __builtin_amdgcn_mfma_f32_32x32x16_bf16(vf, pf, o[dt], 0, 0, 0); } }
;             __builtin_amdgcn_sched_barrier(0);
;         }
;         sum += __shfl_xor(sum, 32);
;         if (un < NU) { const AUnit wq = attn_decode(un, HD0, NH); ATTN_QLOAD(wq); }
.Lattn1_skip3:
	v_mov_b32_e32 v60, v238
.Lattn1_t4f:
	s_sub_i32 s99, s99, 32
	s_cmp_gt_i32 s98, s99
	s_cbranch_scc1 .Lattn1_skip4
	ds_read_b128 v[48:51], v207
	ds_read_b128 v[52:55], v207 offset:32
	s_waitcnt lgkmcnt(1)
	v_mfma_f32_32x32x16_bf16 v[0:15], v[48:51], v[88:91], v[0:15]
	ds_read_b128 v[48:51], v207 offset:64
	ds_read_b128 v[56:59], v207 offset:96
	s_waitcnt lgkmcnt(2)
	v_mfma_f32_32x32x16_bf16 v[0:15], v[52:55], v[92:95], v[0:15]
	s_waitcnt lgkmcnt(1)
	v_mfma_f32_32x32x16_bf16 v[0:15], v[48:51], v[100:103], v[0:15]
	s_waitcnt lgkmcnt(0)
	v_mfma_f32_32x32x16_bf16 v[0:15], v[56:59], v[108:111], v[0:15]
	s_nop 11
	v_fma_f32 v0, v224, |v244|, v0
	v_fma_f32 v1, v224, |v245|, v1
	v_fma_f32 v2, v224, |v246|, v2
	v_fma_f32 v3, v224, |v247|, v3
	v_fma_f32 v4, v224, |v248|, v4
	v_fma_f32 v5, v224, |v249|, v5
	v_exp_f32_e32 v49, v1
	v_mov_b32_e32 v1, v5
	v_exp_f32_e32 v53, v1
	v_exp_f32_e32 v50, v2
	v_fma_f32 v1, v224, |v250|, v6
	v_exp_f32_e32 v48, v0
	v_exp_f32_e32 v54, v1
	v_fma_f32 v1, v224, |v251|, v7
	v_exp_f32_e32 v51, v3
	v_exp_f32_e32 v52, v4
	v_add_f32_e32 v0, 0, v48
	v_exp_f32_e32 v7, v1
	v_add_f32_e32 v0, v49, v0
	v_add_f32_e32 v0, v50, v0
	v_fma_f32 v1, v224, |v252|, v8
	v_add_f32_e32 v0, v51, v0
	v_add_f32_e32 v0, v52, v0
	v_exp_f32_e32 v55, v1
	v_add_f32_e32 v0, v53, v0
	v_add_f32_e32 v0, v54, v0
	v_add_f32_e32 v0, v7, v0
	v_add_f32_e32 v56, v55, v0
	v_fma_f32 v0, v224, |v253|, v9
	v_exp_f32_e32 v57, v0
	v_fma_f32 v0, v224, |v254|, v10
	v_exp_f32_e32 v58, v0
	v_fma_f32 v0, v224, |v255|, v11
	v_exp_f32_e32 v59, v0
	v_fma_f32 v0, v224, |v164|, v12
	v_exp_f32_e32 v12, v0
	v_fma_f32 v0, v224, |v165|, v13
	v_exp_f32_e32 v13, v0
	v_fma_f32 v4, v224, |v166|, v14
	ds_read_b64_tr_b16 v[0:1], v208 offset:55296
	ds_read_b64_tr_b16 v[2:3], v208 offset:56832
	ds_read_b64_tr_b16 v[10:11], v208 offset:56896
	ds_read_b64_tr_b16 v[8:9], v208 offset:55360
	v_exp_f32_e32 v14, v4
	v_cvt_pk_bf16_f32 v4, v48, v49
	v_cvt_pk_bf16_f32 v5, v50, v51
	v_cvt_pk_bf16_f32 v6, v52, v53
	v_cvt_pk_bf16_f32 v7, v54, v7
	s_waitcnt lgkmcnt(2)
	s_nop 0
	v_mfma_f32_32x32x16_bf16 v[32:47], v[0:3], v[4:7], v[32:47]
	v_fma_f32 v15, v224, |v167|, v15
	ds_read_b64_tr_b16 v[0:1], v208 offset:58368
	ds_read_b64_tr_b16 v[2:3], v208 offset:59904
	v_exp_f32_e32 v15, v15
	s_waitcnt lgkmcnt(2)
	v_mfma_f32_32x32x16_bf16 v[16:31], v[8:11], v[4:7], v[16:31]
	ds_read_b64_tr_b16 v[10:11], v208 offset:59968
	ds_read_b64_tr_b16 v[8:9], v208 offset:58432
	v_cvt_pk_bf16_f32 v4, v55, v57
	v_cvt_pk_bf16_f32 v5, v58, v59
	v_cvt_pk_bf16_f32 v6, v12, v13
	v_cvt_pk_bf16_f32 v7, v14, v15
	s_waitcnt lgkmcnt(2)
	s_nop 0
	v_mfma_f32_32x32x16_bf16 v[32:47], v[0:3], v[4:7], v[32:47]
	v_add_f32_e32 v0, v57, v56
	v_add_f32_e32 v0, v58, v0
	v_add_f32_e32 v0, v59, v0
	v_add_f32_e32 v0, v12, v0
	v_add_f32_e32 v0, v13, v0
	v_add_f32_e32 v0, v14, v0
	v_add_f32_e32 v0, v15, v0
	s_waitcnt lgkmcnt(0)
	v_mfma_f32_32x32x16_bf16 v[16:31], v[8:11], v[4:7], v[16:31]
	v_add_f32_e32 v0, v60, v0
	s_branch .Lattn1_end
.Lattn1_skip4:
	v_mov_b32_e32 v0, v60
.Lattn1_end:
	ds_bpermute_b32 v1, v153, v0
	s_andn2_b64 vcc, exec, s[72:73]
	s_cbranch_vccnz .LBB0_284
	s_ashr_i32 s7, s69, 5
	s_lshr_b32 s8, s7, 28
	s_add_i32 s8, s7, s8
	s_and_b32 s8, s8, -16
	s_sub_i32 s7, s7, s8
	s_add_i32 s7, s7, 8
	s_ashr_i32 s8, s69, 31
	s_ashr_i32 s9, s7, 2
	s_lshr_b32 s8, s8, 23
	s_and_b32 s9, s9, -2
	s_add_i32 s8, s69, s8
	s_lshr_b32 s10, 32, s9
	s_and_b32 s6, s69, 31
	s_ashr_i32 s8, s8, 9
	s_lshr_b32 s11, 0x2000, s9
	s_sub_i32 s9, 5, s9
	s_add_i32 s10, s10, -1
	s_lshr_b32 s9, s6, s9
	s_and_b32 s6, s10, s6
	s_mul_i32 s8, s8, 24
	s_lshl_b32 s10, s6, 8
	s_add_i32 s6, s7, s8
	s_mul_i32 s9, s9, s11
	s_ashr_i32 s7, s6, 31
	s_add_i32 s10, s10, s9
	v_add_u32_e32 v2, s10, v145
	s_lshl_b64 s[6:7], s[6:7], 20
	v_ashrrev_i32_e32 v3, 31, v2
	s_add_u32 s6, s40, s6
	s_addc_u32 s7, s41, s7
	v_lshlrev_b64 v[2:3], 7, v[2:3]
	v_lshl_add_u64 v[2:3], s[6:7], 0, v[2:3]
	v_lshl_add_u64 v[2:3], v[148:149], 1, v[2:3]
	global_load_dwordx4 v[88:91], v[2:3], off
	global_load_dwordx4 v[92:95], v[2:3], off offset:32
	global_load_dwordx4 v[100:103], v[2:3], off offset:64
	global_load_dwordx4 v[108:111], v[2:3], off offset:96
